# weight-conversion stagger split by XCD halves (XCDs 0-3 convert first, 4-7 last) instead of alternating workgroups within each XCD
# baseline (speedup 1.0000x reference)
; #define LAS __attribute__((address_space(3)))
; __device__ __forceinline__ int hw_lane() { int l; asm volatile("v_mbcnt_lo_u32_b32 %0, -1, 0\n\tv_mbcnt_hi_u32_b32 %0, -1, %0" : "=v"(l)); return l; }
; __device__ __forceinline__ TrArgs tr_decode(const Params& p, int it) {
;     TrArgs a; int r = it;
;     if (r < 2 * TR_I_GU) { const bool second = r >= TR_I_GU; if (second) r -= TR_I_GU;
;         const int kb = r / 352, nb = r % 352, pn = nb >> 3, sub = nb & 7;
;         a.W = sub < 4 ? (second ? p.wg2 : p.wg1) : (second ? p.wu2 : p.wu1); a.gk = second ? p.n2 : p.n1; a.WT = (bf16_t*)(p.ws + (second ? WS_WGU2 : WS_WGU1));
;         a.ldsrc = FF; a.k0 = 64 * kb; a.srccol0 = 128 * pn + 32 * (sub & 3); a.nvalid = 32; a.K = DM; a.dstrow0 = 32 * nb; return a; }
;     r -= 2 * TR_I_GU;
;     if (r < 2 * TR_I_D) { const bool second = r >= TR_I_D; if (second) r -= TR_I_D;
;         a.W = second ? p.wd2 : p.wd1; a.gk = nullptr; a.WT = (bf16_t*)(p.ws + (second ? WS_WD2 : WS_WD1));
;         a.ldsrc = DM; a.k0 = 64 * (r / 64); a.srccol0 = 32 * (r % 64); a.nvalid = 32; a.K = FF; a.dstrow0 = 32 * (r % 64); return a; }
;     r -= 2 * TR_I_D;
;     if (r < TR_I_IN) { const int kb = r / 200, nb = r % 200, n0 = 32 * nb; int src, nv;
;         if (n0 < 2048) { src = n0; nv = 32; } else if (n0 < 6144) { src = n0 + 16; nv = 32; } else if (n0 == 6144) { src = 2048; nv = 16; } else { src = 0; nv = 0; }
;         a.W = p.win; a.gk = p.nmix; a.WT = (bf16_t*)(p.ws + WS_WIN); a.ldsrc = DIN_SRC; a.k0 = 64 * kb; a.srccol0 = src; a.nvalid = nv; a.K = DM; a.dstrow0 = n0; return a; }
; __global__ void __launch_bounds__(512) fwd_kernel(Params p) {
;     ...
;       const bool stag = (G == 256), early = (((int)blockIdx.x >> 3) & 1) == 0;
;       if (stag && early) { convert_items(p, (LAS float*)(lds + wave * 16384), hw_lane(), TR_I_GU + gw, TR_NITEMS, NGW); __syncthreads(); }
.LBB0_133:
	s_or_b64 exec, exec, s[2:3]
	s_bitcmp0_b32 s66, 2
	s_cselect_b64 s[2:3], -1, 0
	s_and_b64 s[4:5], s[2:3], s[8:9]
	s_andn2_b64 vcc, exec, s[4:5]
	s_waitcnt lgkmcnt(0)
	s_barrier
	s_cbranch_vccnz .LBB0_175
	s_cmpk_gt_i32 s20, 0x78ff
	v_mbcnt_lo_u32_b32 v1, -1, 0
	v_mbcnt_hi_u32_b32 v1, -1, v1
	s_cbranch_scc1 .LBB0_174
	s_add_i32 s11, s20, 0x2c00
	s_cmpk_gt_i32 s20, 0x2bff
	s_cbranch_scc0 .LBB0_140
	s_cmpk_gt_u32 s11, 0x83ff
	s_cbranch_scc0 .LBB0_141
	s_cmpk_gt_u32 s11, 0x9cff
	s_cbranch_scc1 .LBB0_138
	s_getpc_b64 s[98:99]
